# v87 + workgroup 0 (which zeroes the barrier words first) hands its 8 w_in conversion tiles to workgroup 255 (which has none)
# baseline (speedup 1.0000x reference)
; #define LAS __attribute__((address_space(3)))
; __device__ __forceinline__ void transpose_tile(const float* __restrict__ W, int K, int N, bf16* __restrict__ WT, const float* __restrict__ ga, const float* __restrict__ gb, int gsplit, LAS float* scr, int item, int lane) {
;     const int nkb = K / 64, nb = item / nkb, kb = item % nkb, k0 = 64 * kb, n0 = 64 * nb;
;     const int c = lane & 15, kq = lane >> 4;
;     f32x4 v[16];
; #pragma unroll
;     for (int i = 0; i < 16; ++i) v[i] = __builtin_nontemporal_load((const f32x4*)(W + (size_t)(k0 + 4 * i + kq) * N + n0 + 4 * c));
; __global__ void __launch_bounds__(NT, 2) fwd_mega(Args A) {
;     ...
;         const int gw = vcu * NW + wave, NGW = G * NW;
;         LAS float* scr = (LAS float*)(lds + wave * 16640);
;         constexpr int I_IN = (D / 64) * (INW / 64);
;         for (int it = gw; it < I_IN; it += NGW) transpose_tile(A.w_in, D, INW, WinT, A.g_mix, A.g_mix, D, scr, it, lane);
.LBB0_24:
	v_writelane_b32 v255, s54, 1
	s_nop 1
	v_writelane_b32 v255, s55, 2
	s_add_u32 s54, s28, 0x300000
	s_addc_u32 s55, s29, 0
	s_lshr_b32 s1, s58, 6
	s_lshl_b32 s0, s3, 3
	s_add_i32 s58, s0, s1
	s_mul_i32 s0, s1, 0x4100
	s_lshl_b32 s52, s30, 3
	v_writelane_b32 v255, s1, 3
	s_add_i32 s0, s0, 0
	v_writelane_b32 v255, s0, 4
	s_cmpk_gt_i32 s58, 0x6ff
	v_and_b32_e32 v152, 63, v160
	s_mov_b32 s60, s58
	s_add_i32 s86, s58, 0xfffff808
	s_cmp_ge_u32 s58, 0x7f8
	s_cselect_b32 s60, s86, s60
	s_cmp_lt_u32 s58, 8
	s_cselect_b32 s60, 0x7fff, s60
	s_nop 0
	s_mov_b32 s61, s52
	s_movk_i32 s62, 0x700
	s_cmp_ge_u32 s60, s62
	s_cbranch_scc1 .Lcva_end
	v_readlane_b32 s63, v255, 3
	v_and_b32_e32 v122, 63, v160
	v_and_b32_e32 v112, 15, v122
	v_lshlrev_b32_e32 v112, 4, v112
	v_lshrrev_b32_e32 v113, 4, v122
	v_lshlrev_b32_e32 v114, 2, v113
	v_and_b32_e32 v115, 7, v122
	v_lshrrev_b32_e32 v116, 3, v122
	s_mulk_i32 s63, 0x4100
	s_movk_i32 s80, 0x104
	v_mad_u32_u24 v117, v113, s80, v112
	v_add_u32_e32 v117, s63, v117
	s_movk_i32 s80, 0x820
	v_lshlrev_b32_e32 v119, 2, v116
	v_mad_u32_u24 v118, v115, s80, v119
	v_add_u32_e32 v118, s63, v118
	v_add_u32_e32 v119, 0x400, v118
	v_lshlrev_b32_e32 v115, 4, v115
	s_mov_b32 s75, s60
	s_branch .Lcva_p0_m0
